# p2epi
# speedup vs baseline: 1.0103x; 1.0079x over previous
; template <int EPI>
; __device__ __forceinline__ void gemm_phase(const u16* __restrict__ A, const u16* __restrict__ Bt, const int K,
;                                            const int nN, char* shm, const EpiArgs& ea) {
;     ...
;               float rs = 0.f, rq = 0.f;
; #pragma unroll
;               for (int bj = 0; bj < 2; ++bj) {
;                 uint2 pk[2];
; #pragma unroll
;                 for (int n = 0; n < 2; ++n) {
;                   const int col = cb + bj * 128 + n * 16;
;                   f32x4 c = acc[ai][bj][m][n];
;                   float h[4];
;                   if (EPI == EPI_FFN1) {
;                     float4 rv = *(const float4*)(ea.res + (size_t)row * DM + col);
;                     h[0] = rv.x; h[1] = rv.y; h[2] = rv.z; h[3] = rv.w;
;                   } else {
;                     uint2 yv = *(const uint2*)((const char*)ea.yb + tl_off(row, col, DM >> 6));
;                     float4 gv = *(const float4*)(ea.lng + col);
;                     float4 bv = *(const float4*)(ea.lnb + col);
;                     h[0] = (bf_lo(yv.x) - mu) * rstd * gv.x + bv.x; h[1] = (bf_hi(yv.x) - mu) * rstd * gv.y + bv.y;
;                     h[2] = (bf_lo(yv.y) - mu) * rstd * gv.z + bv.z; h[3] = (bf_hi(yv.y) - mu) * rstd * gv.w + bv.w;
;                   }
;                   float y[4];
;                   if (EPI == EPI_OUT) {
;                     float4 bo = *(const float4*)(ea.bias + col);
;                     y[0] = ALPHA * h[0] + c[0] + bo.x; y[1] = ALPHA * h[1] + c[1] + bo.y;
;                     y[2] = ALPHA * h[2] + c[2] + bo.z; y[3] = ALPHA * h[3] + c[3] + bo.w;
;                   } else {
; #pragma unroll
;                     for (int j = 0; j < 4; ++j) y[j] = ALPHA * h[j] + 0.5f * c[j];
;                   }
;                   if (EPI == EPI_FFN2) {
;                     *(float4*)(ea.outf + (size_t)row * DM + col) = make_float4(y[0], y[1], y[2], y[3]);
;                   } else {
;                     pk[n] = make_uint2(pack2(y[0], y[1]), pack2(y[2], y[3]));
;                     float q0 = bf_lo(pk[n].x), q1 = bf_hi(pk[n].x), q2 = bf_lo(pk[n].y), q3 = bf_hi(pk[n].y);
;                     rs += (q0 + q1) + (q2 + q3);
;                     rq += (q0 * q0 + q1 * q1) + (q2 * q2 + q3 * q3);
;                   }
;                 }
;                 if (EPI != EPI_FFN2) {
.LBB0_236:
	s_lshr_b32 s98, s69, 7
	s_mul_i32 s98, s98, 0x84000
	s_lshr_b32 s99, s33, 6
	s_lshl_b32 s99, s99, 14
	s_add_i32 s98, s98, s99
	s_add_i32 s99, s33, s65
	v_add_u32_e32 v146, s69, v135
	v_add_u32_e32 v147, s99, v136
	v_lshlrev_b32_e32 v151, 2, v147
	v_lshl_add_u32 v148, v146, 13, v151
	global_load_dwordx4 v[176:179], v148, s[36:37]
	global_load_dwordx4 v[180:183], v148, s[36:37] offset:64
	global_load_dwordx4 v[184:187], v148, s[36:37] offset:512
	global_load_dwordx4 v[188:191], v148, s[36:37] offset:576
	v_add_u32_e32 v153, 0x20000, v148
	global_load_dwordx4 v[192:195], v153, s[36:37]
	global_load_dwordx4 v[196:199], v153, s[36:37] offset:64
	global_load_dwordx4 v[200:203], v153, s[36:37] offset:512
	global_load_dwordx4 v[204:207], v153, s[36:37] offset:576
	v_add_u32_e32 v153, 0x40000, v148
	global_load_dwordx4 v[208:211], v153, s[36:37]
	global_load_dwordx4 v[212:215], v153, s[36:37] offset:64
	global_load_dwordx4 v[216:219], v153, s[36:37] offset:512
	global_load_dwordx4 v[220:223], v153, s[36:37] offset:576
	v_add_u32_e32 v153, 0x60000, v148
	global_load_dwordx4 v[224:227], v153, s[36:37]
	global_load_dwordx4 v[228:231], v153, s[36:37] offset:64
	global_load_dwordx4 v[232:235], v153, s[36:37] offset:512
	global_load_dwordx4 v[236:239], v153, s[36:37] offset:576
	v_lshlrev_b32_e32 v150, 3, v146
	v_and_b32_e32 v151, 15, v174
	v_lshlrev_b32_e32 v149, 6, v151
	v_and_b32_e32 v151, 32, v174
	v_lshrrev_b32_e32 v151, 1, v151
	v_or_b32_e32 v149, v149, v151
	v_lshrrev_b32_e32 v151, 1, v174
	v_xor_b32_e32 v151, v151, v174
	v_and_b32_e32 v151, 8, v151
	v_lshl_or_b32 v149, v151, 2, v149
	v_and_b32_e32 v151, 64, v174
	v_lshl_or_b32 v149, v151, 4, v149
	v_and_b32_e32 v151, 0x80, v174
	v_lshl_or_b32 v149, v151, 7, v149
	v_and_b32_e32 v151, 0x100, v174
	v_lshl_or_b32 v149, v151, 5, v149
	v_add_u32_e32 v149, s98, v149
	v_mov_b32_e32 v154, v149
	v_mov_b32_e32 v164, 0
	v_mov_b32_e32 v165, 0
	s_waitcnt vmcnt(15)
	v_pk_mul_f32 v[176:177], v[176:177], s[34:35] op_sel_hi:[1,0]
	v_pk_mul_f32 v[178:179], v[178:179], s[34:35] op_sel_hi:[1,0]
	v_pk_fma_f32 v[120:121], v[120:121], 0.5, v[176:177] op_sel_hi:[1,0,1]
	v_pk_fma_f32 v[122:123], v[122:123], 0.5, v[178:179] op_sel_hi:[1,0,1]
	v_cvt_pk_bf16_f32 v240, v120, v121
	v_cvt_pk_bf16_f32 v241, v122, v123
	v_lshlrev_b32_e32 v156, 16, v240
	v_and_b32_e32 v157, 0xffff0000, v240
	v_lshlrev_b32_e32 v158, 16, v241
	v_and_b32_e32 v159, 0xffff0000, v241
	v_add_f32_e32 v164, v164, v156
	v_fmac_f32_e32 v165, v156, v156
	v_add_f32_e32 v164, v164, v157
	v_fmac_f32_e32 v165, v157, v157
	v_add_f32_e32 v164, v164, v158
	v_fmac_f32_e32 v165, v158, v158
	v_add_f32_e32 v164, v164, v159
	v_fmac_f32_e32 v165, v159, v159
	s_waitcnt vmcnt(14)
	v_pk_mul_f32 v[180:181], v[180:181], s[34:35] op_sel_hi:[1,0]
	v_pk_mul_f32 v[182:183], v[182:183], s[34:35] op_sel_hi:[1,0]
	v_pk_fma_f32 v[124:125], v[124:125], 0.5, v[180:181] op_sel_hi:[1,0,1]
	v_pk_fma_f32 v[126:127], v[126:127], 0.5, v[182:183] op_sel_hi:[1,0,1]
	v_cvt_pk_bf16_f32 v242, v124, v125
	v_cvt_pk_bf16_f32 v243, v126, v127
	v_lshlrev_b32_e32 v156, 16, v242
	v_and_b32_e32 v157, 0xffff0000, v242
	v_lshlrev_b32_e32 v158, 16, v243
	v_and_b32_e32 v159, 0xffff0000, v243
	v_add_f32_e32 v164, v164, v156
	v_fmac_f32_e32 v165, v156, v156
	v_add_f32_e32 v164, v164, v157
	v_fmac_f32_e32 v165, v157, v157
	v_add_f32_e32 v164, v164, v158
	v_fmac_f32_e32 v165, v158, v158
	v_add_f32_e32 v164, v164, v159
	v_fmac_f32_e32 v165, v159, v159
	v_permlane16_swap_b32_e32 v240, v242
	v_permlane16_swap_b32_e32 v241, v243
	global_store_dwordx4 v154, v[240:243], s[18:19]
	s_waitcnt vmcnt(14)
	v_pk_mul_f32 v[184:185], v[184:185], s[34:35] op_sel_hi:[1,0]
	v_pk_mul_f32 v[186:187], v[186:187], s[34:35] op_sel_hi:[1,0]
	v_pk_fma_f32 v[112:113], v[112:113], 0.5, v[184:185] op_sel_hi:[1,0,1]
	v_pk_fma_f32 v[114:115], v[114:115], 0.5, v[186:187] op_sel_hi:[1,0,1]
	v_cvt_pk_bf16_f32 v168, v112, v113
	v_cvt_pk_bf16_f32 v169, v114, v115
	v_lshlrev_b32_e32 v156, 16, v168
	v_and_b32_e32 v157, 0xffff0000, v168
	v_lshlrev_b32_e32 v158, 16, v169
	v_and_b32_e32 v159, 0xffff0000, v169
	v_add_f32_e32 v164, v164, v156
	v_fmac_f32_e32 v165, v156, v156
	v_add_f32_e32 v164, v164, v157
	v_fmac_f32_e32 v165, v157, v157
	v_add_f32_e32 v164, v164, v158
	v_fmac_f32_e32 v165, v158, v158
	v_add_f32_e32 v164, v164, v159
	v_fmac_f32_e32 v165, v159, v159
	s_waitcnt vmcnt(13)
	v_pk_mul_f32 v[188:189], v[188:189], s[34:35] op_sel_hi:[1,0]
	v_pk_mul_f32 v[190:191], v[190:191], s[34:35] op_sel_hi:[1,0]
	v_pk_fma_f32 v[116:117], v[116:117], 0.5, v[188:189] op_sel_hi:[1,0,1]
	v_pk_fma_f32 v[118:119], v[118:119], 0.5, v[190:191] op_sel_hi:[1,0,1]
	v_cvt_pk_bf16_f32 v170, v116, v117
	v_cvt_pk_bf16_f32 v171, v118, v119
	v_lshlrev_b32_e32 v156, 16, v170
	v_and_b32_e32 v157, 0xffff0000, v170
	v_lshlrev_b32_e32 v158, 16, v171
	v_and_b32_e32 v159, 0xffff0000, v171
	v_add_f32_e32 v164, v164, v156
	v_fmac_f32_e32 v165, v156, v156
	v_add_f32_e32 v164, v164, v157
	v_fmac_f32_e32 v165, v157, v157
	v_add_f32_e32 v164, v164, v158
	v_fmac_f32_e32 v165, v158, v158
	v_add_f32_e32 v164, v164, v159
	v_fmac_f32_e32 v165, v159, v159
	v_permlane16_swap_b32_e32 v168, v170
	v_permlane16_swap_b32_e32 v169, v171
	v_add_u32_e32 v152, 0x8000, v154
	global_store_dwordx4 v152, v[168:171], s[18:19]
	v_add_u32_e32 v153, 0x100000, v148
	global_load_dwordx4 v[176:179], v153, s[36:37]
	global_load_dwordx4 v[180:183], v153, s[36:37] offset:64
	global_load_dwordx4 v[184:187], v153, s[36:37] offset:512
	global_load_dwordx4 v[188:191], v153, s[36:37] offset:576
	v_mov_b32_e32 v166, v164
	v_mov_b32_e32 v167, v165
	s_nop 0
	v_permlane16_swap_b32_e32 v164, v166
	v_permlane16_swap_b32_e32 v165, v167
	v_add_f32_e32 v164, v164, v166
	v_add_f32_e32 v165, v165, v167
	v_mov_b32_e32 v166, v164
	v_mov_b32_e32 v167, v165
	s_nop 0
	v_permlane32_swap_b32_e32 v164, v166
	v_permlane32_swap_b32_e32 v165, v167
	v_add_f32_e32 v164, v164, v166
	v_add_f32_e32 v165, v165, v167
	s_and_saveexec_b64 s[26:27], s[6:7]
	global_atomic_add_f32 v150, v164, s[28:29]
	global_atomic_add_f32 v150, v165, s[28:29] offset:4
	s_or_b64 exec, exec, s[26:27]
	v_add_u32_e32 v154, 0x800, v149
	v_mov_b32_e32 v164, 0
	v_mov_b32_e32 v165, 0
	s_waitcnt vmcnt(19)
; template <int EPI>
; __device__ __forceinline__ void gemm_phase(const u16* __restrict__ A, const u16* __restrict__ Bt, const int K,
;                                            const int nN, char* shm, const EpiArgs& ea) {
;     ...
;               for (int bj = 0; bj < 2; ++bj) {
;                 uint2 pk[2];
; #pragma unroll
;                 for (int n = 0; n < 2; ++n) {
;                   const int col = cb + bj * 128 + n * 16;
;                   f32x4 c = acc[ai][bj][m][n];
;                   float h[4];
;                   if (EPI == EPI_FFN1) {
;                     float4 rv = *(const float4*)(ea.res + (size_t)row * DM + col);
;                     h[0] = rv.x; h[1] = rv.y; h[2] = rv.z; h[3] = rv.w;
;                   } else {
;                     uint2 yv = *(const uint2*)((const char*)ea.yb + tl_off(row, col, DM >> 6));
;                     float4 gv = *(const float4*)(ea.lng + col);
;                     float4 bv = *(const float4*)(ea.lnb + col);
;                     h[0] = (bf_lo(yv.x) - mu) * rstd * gv.x + bv.x; h[1] = (bf_hi(yv.x) - mu) * rstd * gv.y + bv.y;
;                     h[2] = (bf_lo(yv.y) - mu) * rstd * gv.z + bv.z; h[3] = (bf_hi(yv.y) - mu) * rstd * gv.w + bv.w;
;                   }
;                   float y[4];
;                   if (EPI == EPI_OUT) {
;                     float4 bo = *(const float4*)(ea.bias + col);
;                     y[0] = ALPHA * h[0] + c[0] + bo.x; y[1] = ALPHA * h[1] + c[1] + bo.y;
;                     y[2] = ALPHA * h[2] + c[2] + bo.z; y[3] = ALPHA * h[3] + c[3] + bo.w;
;                   } else {
; #pragma unroll
;                     for (int j = 0; j < 4; ++j) y[j] = ALPHA * h[j] + 0.5f * c[j];
;                   }
;                   if (EPI == EPI_FFN2) {
;                     *(float4*)(ea.outf + (size_t)row * DM + col) = make_float4(y[0], y[1], y[2], y[3]);
;                   } else {
;                     pk[n] = make_uint2(pack2(y[0], y[1]), pack2(y[2], y[3]));
;                     float q0 = bf_lo(pk[n].x), q1 = bf_hi(pk[n].x), q2 = bf_lo(pk[n].y), q3 = bf_hi(pk[n].y);
;                     rs += (q0 + q1) + (q2 + q3);
;                     rq += (q0 * q0 + q1 * q1) + (q2 * q2 + q3 * q3);
;                   }
;                 }
;                 if (EPI != EPI_FFN2) {
;                   const uint4 w = widen16(pk[0], pk[1]);
	v_pk_mul_f32 v[192:193], v[192:193], s[34:35] op_sel_hi:[1,0]
	v_pk_mul_f32 v[194:195], v[194:195], s[34:35] op_sel_hi:[1,0]
	v_pk_fma_f32 v[104:105], v[104:105], 0.5, v[192:193] op_sel_hi:[1,0,1]
	v_pk_fma_f32 v[106:107], v[106:107], 0.5, v[194:195] op_sel_hi:[1,0,1]
	v_cvt_pk_bf16_f32 v240, v104, v105
	v_cvt_pk_bf16_f32 v241, v106, v107
	v_lshlrev_b32_e32 v156, 16, v240
	v_and_b32_e32 v157, 0xffff0000, v240
	v_lshlrev_b32_e32 v158, 16, v241
	v_and_b32_e32 v159, 0xffff0000, v241
	v_add_f32_e32 v164, v164, v156
	v_fmac_f32_e32 v165, v156, v156
	v_add_f32_e32 v164, v164, v157
	v_fmac_f32_e32 v165, v157, v157
	v_add_f32_e32 v164, v164, v158
	v_fmac_f32_e32 v165, v158, v158
	v_add_f32_e32 v164, v164, v159
	v_fmac_f32_e32 v165, v159, v159
	s_waitcnt vmcnt(18)
	v_pk_mul_f32 v[196:197], v[196:197], s[34:35] op_sel_hi:[1,0]
	v_pk_mul_f32 v[198:199], v[198:199], s[34:35] op_sel_hi:[1,0]
	v_pk_fma_f32 v[108:109], v[108:109], 0.5, v[196:197] op_sel_hi:[1,0,1]
	v_pk_fma_f32 v[110:111], v[110:111], 0.5, v[198:199] op_sel_hi:[1,0,1]
	v_cvt_pk_bf16_f32 v242, v108, v109
	v_cvt_pk_bf16_f32 v243, v110, v111
	v_lshlrev_b32_e32 v156, 16, v242
	v_and_b32_e32 v157, 0xffff0000, v242
	v_lshlrev_b32_e32 v158, 16, v243
	v_and_b32_e32 v159, 0xffff0000, v243
	v_add_f32_e32 v164, v164, v156
	v_fmac_f32_e32 v165, v156, v156
	v_add_f32_e32 v164, v164, v157
	v_fmac_f32_e32 v165, v157, v157
	v_add_f32_e32 v164, v164, v158
	v_fmac_f32_e32 v165, v158, v158
	v_add_f32_e32 v164, v164, v159
	v_fmac_f32_e32 v165, v159, v159
	v_permlane16_swap_b32_e32 v240, v242
	v_permlane16_swap_b32_e32 v241, v243
	global_store_dwordx4 v154, v[240:243], s[18:19]
	s_waitcnt vmcnt(18)
	v_pk_mul_f32 v[200:201], v[200:201], s[34:35] op_sel_hi:[1,0]
	v_pk_mul_f32 v[202:203], v[202:203], s[34:35] op_sel_hi:[1,0]
	v_pk_fma_f32 v[96:97], v[96:97], 0.5, v[200:201] op_sel_hi:[1,0,1]
	v_pk_fma_f32 v[98:99], v[98:99], 0.5, v[202:203] op_sel_hi:[1,0,1]
	v_cvt_pk_bf16_f32 v168, v96, v97
	v_cvt_pk_bf16_f32 v169, v98, v99
	v_lshlrev_b32_e32 v156, 16, v168
	v_and_b32_e32 v157, 0xffff0000, v168
	v_lshlrev_b32_e32 v158, 16, v169
	v_and_b32_e32 v159, 0xffff0000, v169
	v_add_f32_e32 v164, v164, v156
	v_fmac_f32_e32 v165, v156, v156
	v_add_f32_e32 v164, v164, v157
	v_fmac_f32_e32 v165, v157, v157
	v_add_f32_e32 v164, v164, v158
	v_fmac_f32_e32 v165, v158, v158
	v_add_f32_e32 v164, v164, v159
	v_fmac_f32_e32 v165, v159, v159
	s_waitcnt vmcnt(17)
	v_pk_mul_f32 v[204:205], v[204:205], s[34:35] op_sel_hi:[1,0]
	v_pk_mul_f32 v[206:207], v[206:207], s[34:35] op_sel_hi:[1,0]
	v_pk_fma_f32 v[100:101], v[100:101], 0.5, v[204:205] op_sel_hi:[1,0,1]
	v_pk_fma_f32 v[102:103], v[102:103], 0.5, v[206:207] op_sel_hi:[1,0,1]
	v_cvt_pk_bf16_f32 v170, v100, v101
	v_cvt_pk_bf16_f32 v171, v102, v103
	v_lshlrev_b32_e32 v156, 16, v170
	v_and_b32_e32 v157, 0xffff0000, v170
	v_lshlrev_b32_e32 v158, 16, v171
	v_and_b32_e32 v159, 0xffff0000, v171
	v_add_f32_e32 v164, v164, v156
	v_fmac_f32_e32 v165, v156, v156
	v_add_f32_e32 v164, v164, v157
	v_fmac_f32_e32 v165, v157, v157
	v_add_f32_e32 v164, v164, v158
	v_fmac_f32_e32 v165, v158, v158
	v_add_f32_e32 v164, v164, v159
	v_fmac_f32_e32 v165, v159, v159
	v_permlane16_swap_b32_e32 v168, v170
	v_permlane16_swap_b32_e32 v169, v171
	v_add_u32_e32 v152, 0x8000, v154
	global_store_dwordx4 v152, v[168:171], s[18:19]
	v_add_u32_e32 v153, 0x120000, v148
	global_load_dwordx4 v[192:195], v153, s[36:37]
	global_load_dwordx4 v[196:199], v153, s[36:37] offset:64
	global_load_dwordx4 v[200:203], v153, s[36:37] offset:512
	global_load_dwordx4 v[204:207], v153, s[36:37] offset:576
	v_mov_b32_e32 v166, v164
	v_mov_b32_e32 v167, v165
	s_nop 0
	v_permlane16_swap_b32_e32 v164, v166
	v_permlane16_swap_b32_e32 v165, v167
	v_add_f32_e32 v164, v164, v166
	v_add_f32_e32 v165, v165, v167
	v_mov_b32_e32 v166, v164
	v_mov_b32_e32 v167, v165
	s_nop 0
	v_permlane32_swap_b32_e32 v164, v166
	v_permlane32_swap_b32_e32 v165, v167
	v_add_f32_e32 v164, v164, v166
	v_add_f32_e32 v165, v165, v167
	s_and_saveexec_b64 s[26:27], s[6:7]
	global_atomic_add_f32 v150, v164, s[28:29] offset:128
	global_atomic_add_f32 v150, v165, s[28:29] offset:132
	s_or_b64 exec, exec, s[26:27]
	v_add_u32_e32 v154, 0x1000, v149
	v_mov_b32_e32 v164, 0
	v_mov_b32_e32 v165, 0
	s_waitcnt vmcnt(23)
	v_pk_mul_f32 v[208:209], v[208:209], s[34:35] op_sel_hi:[1,0]
	v_pk_mul_f32 v[210:211], v[210:211], s[34:35] op_sel_hi:[1,0]
	v_pk_fma_f32 v[88:89], v[88:89], 0.5, v[208:209] op_sel_hi:[1,0,1]
	v_pk_fma_f32 v[90:91], v[90:91], 0.5, v[210:211] op_sel_hi:[1,0,1]
	v_cvt_pk_bf16_f32 v240, v88, v89
	v_cvt_pk_bf16_f32 v241, v90, v91
	v_lshlrev_b32_e32 v156, 16, v240
	v_and_b32_e32 v157, 0xffff0000, v240
	v_lshlrev_b32_e32 v158, 16, v241
	v_and_b32_e32 v159, 0xffff0000, v241
	v_add_f32_e32 v164, v164, v156
	v_fmac_f32_e32 v165, v156, v156
	v_add_f32_e32 v164, v164, v157
	v_fmac_f32_e32 v165, v157, v157
	v_add_f32_e32 v164, v164, v158
	v_fmac_f32_e32 v165, v158, v158
	v_add_f32_e32 v164, v164, v159
	v_fmac_f32_e32 v165, v159, v159
	s_waitcnt vmcnt(22)
	v_pk_mul_f32 v[212:213], v[212:213], s[34:35] op_sel_hi:[1,0]
	v_pk_mul_f32 v[214:215], v[214:215], s[34:35] op_sel_hi:[1,0]
	v_pk_fma_f32 v[92:93], v[92:93], 0.5, v[212:213] op_sel_hi:[1,0,1]
	v_pk_fma_f32 v[94:95], v[94:95], 0.5, v[214:215] op_sel_hi:[1,0,1]
	v_cvt_pk_bf16_f32 v242, v92, v93
	v_cvt_pk_bf16_f32 v243, v94, v95
	v_lshlrev_b32_e32 v156, 16, v242
	v_and_b32_e32 v157, 0xffff0000, v242
	v_lshlrev_b32_e32 v158, 16, v243
	v_and_b32_e32 v159, 0xffff0000, v243
	v_add_f32_e32 v164, v164, v156
	v_fmac_f32_e32 v165, v156, v156
	v_add_f32_e32 v164, v164, v157
	v_fmac_f32_e32 v165, v157, v157
	v_add_f32_e32 v164, v164, v158
	v_fmac_f32_e32 v165, v158, v158
	v_add_f32_e32 v164, v164, v159
	v_fmac_f32_e32 v165, v159, v159
	v_permlane16_swap_b32_e32 v240, v242
	v_permlane16_swap_b32_e32 v241, v243
	global_store_dwordx4 v154, v[240:243], s[18:19]
	s_waitcnt vmcnt(22)
; template <int EPI>
; __device__ __forceinline__ void gemm_phase(const u16* __restrict__ A, const u16* __restrict__ Bt, const int K,
;                                            const int nN, char* shm, const EpiArgs& ea) {
;     ...
;               for (int bj = 0; bj < 2; ++bj) {
;                 uint2 pk[2];
; #pragma unroll
;                 for (int n = 0; n < 2; ++n) {
;                   const int col = cb + bj * 128 + n * 16;
;                   f32x4 c = acc[ai][bj][m][n];
;                   float h[4];
;                   if (EPI == EPI_FFN1) {
;                     float4 rv = *(const float4*)(ea.res + (size_t)row * DM + col);
;                     h[0] = rv.x; h[1] = rv.y; h[2] = rv.z; h[3] = rv.w;
;                   } else {
;                     uint2 yv = *(const uint2*)((const char*)ea.yb + tl_off(row, col, DM >> 6));
;                     float4 gv = *(const float4*)(ea.lng + col);
;                     float4 bv = *(const float4*)(ea.lnb + col);
;                     h[0] = (bf_lo(yv.x) - mu) * rstd * gv.x + bv.x; h[1] = (bf_hi(yv.x) - mu) * rstd * gv.y + bv.y;
;                     h[2] = (bf_lo(yv.y) - mu) * rstd * gv.z + bv.z; h[3] = (bf_hi(yv.y) - mu) * rstd * gv.w + bv.w;
;                   }
;                   float y[4];
;                   if (EPI == EPI_OUT) {
;                     float4 bo = *(const float4*)(ea.bias + col);
;                     y[0] = ALPHA * h[0] + c[0] + bo.x; y[1] = ALPHA * h[1] + c[1] + bo.y;
;                     y[2] = ALPHA * h[2] + c[2] + bo.z; y[3] = ALPHA * h[3] + c[3] + bo.w;
;                   } else {
; #pragma unroll
;                     for (int j = 0; j < 4; ++j) y[j] = ALPHA * h[j] + 0.5f * c[j];
;                   }
;                   if (EPI == EPI_FFN2) {
;                     *(float4*)(ea.outf + (size_t)row * DM + col) = make_float4(y[0], y[1], y[2], y[3]);
;                   } else {
;                     pk[n] = make_uint2(pack2(y[0], y[1]), pack2(y[2], y[3]));
;                     float q0 = bf_lo(pk[n].x), q1 = bf_hi(pk[n].x), q2 = bf_lo(pk[n].y), q3 = bf_hi(pk[n].y);
;                     rs += (q0 + q1) + (q2 + q3);
;                     rq += (q0 * q0 + q1 * q1) + (q2 * q2 + q3 * q3);
;                   }
;                 }
;                 if (EPI != EPI_FFN2) {
;                   const uint4 w = widen16(pk[0], pk[1]);
	v_pk_mul_f32 v[216:217], v[216:217], s[34:35] op_sel_hi:[1,0]
	v_pk_mul_f32 v[218:219], v[218:219], s[34:35] op_sel_hi:[1,0]
	v_pk_fma_f32 v[80:81], v[80:81], 0.5, v[216:217] op_sel_hi:[1,0,1]
	v_pk_fma_f32 v[82:83], v[82:83], 0.5, v[218:219] op_sel_hi:[1,0,1]
	v_cvt_pk_bf16_f32 v168, v80, v81
	v_cvt_pk_bf16_f32 v169, v82, v83
	v_lshlrev_b32_e32 v156, 16, v168
	v_and_b32_e32 v157, 0xffff0000, v168
	v_lshlrev_b32_e32 v158, 16, v169
	v_and_b32_e32 v159, 0xffff0000, v169
	v_add_f32_e32 v164, v164, v156
	v_fmac_f32_e32 v165, v156, v156
	v_add_f32_e32 v164, v164, v157
	v_fmac_f32_e32 v165, v157, v157
	v_add_f32_e32 v164, v164, v158
	v_fmac_f32_e32 v165, v158, v158
	v_add_f32_e32 v164, v164, v159
	v_fmac_f32_e32 v165, v159, v159
	s_waitcnt vmcnt(21)
	v_pk_mul_f32 v[220:221], v[220:221], s[34:35] op_sel_hi:[1,0]
	v_pk_mul_f32 v[222:223], v[222:223], s[34:35] op_sel_hi:[1,0]
	v_pk_fma_f32 v[84:85], v[84:85], 0.5, v[220:221] op_sel_hi:[1,0,1]
	v_pk_fma_f32 v[86:87], v[86:87], 0.5, v[222:223] op_sel_hi:[1,0,1]
	v_cvt_pk_bf16_f32 v170, v84, v85
	v_cvt_pk_bf16_f32 v171, v86, v87
	v_lshlrev_b32_e32 v156, 16, v170
	v_and_b32_e32 v157, 0xffff0000, v170
	v_lshlrev_b32_e32 v158, 16, v171
	v_and_b32_e32 v159, 0xffff0000, v171
	v_add_f32_e32 v164, v164, v156
	v_fmac_f32_e32 v165, v156, v156
	v_add_f32_e32 v164, v164, v157
	v_fmac_f32_e32 v165, v157, v157
	v_add_f32_e32 v164, v164, v158
	v_fmac_f32_e32 v165, v158, v158
	v_add_f32_e32 v164, v164, v159
	v_fmac_f32_e32 v165, v159, v159
	v_permlane16_swap_b32_e32 v168, v170
	v_permlane16_swap_b32_e32 v169, v171
	v_add_u32_e32 v152, 0x8000, v154
	global_store_dwordx4 v152, v[168:171], s[18:19]
	v_add_u32_e32 v153, 0x140000, v148
	global_load_dwordx4 v[208:211], v153, s[36:37]
	global_load_dwordx4 v[212:215], v153, s[36:37] offset:64
	global_load_dwordx4 v[216:219], v153, s[36:37] offset:512
	global_load_dwordx4 v[220:223], v153, s[36:37] offset:576
	v_mov_b32_e32 v166, v164
	v_mov_b32_e32 v167, v165
	s_nop 0
	v_permlane16_swap_b32_e32 v164, v166
	v_permlane16_swap_b32_e32 v165, v167
	v_add_f32_e32 v164, v164, v166
	v_add_f32_e32 v165, v165, v167
	v_mov_b32_e32 v166, v164
	v_mov_b32_e32 v167, v165
	s_nop 0
	v_permlane32_swap_b32_e32 v164, v166
	v_permlane32_swap_b32_e32 v165, v167
	v_add_f32_e32 v164, v164, v166
	v_add_f32_e32 v165, v165, v167
	s_and_saveexec_b64 s[26:27], s[6:7]
	global_atomic_add_f32 v150, v164, s[28:29] offset:256
	global_atomic_add_f32 v150, v165, s[28:29] offset:260
	s_or_b64 exec, exec, s[26:27]
	v_add_u32_e32 v154, 0x1800, v149
	v_mov_b32_e32 v164, 0
	v_mov_b32_e32 v165, 0
	s_waitcnt vmcnt(27)
	v_pk_mul_f32 v[224:225], v[224:225], s[34:35] op_sel_hi:[1,0]
	v_pk_mul_f32 v[226:227], v[226:227], s[34:35] op_sel_hi:[1,0]
	v_pk_fma_f32 v[72:73], v[72:73], 0.5, v[224:225] op_sel_hi:[1,0,1]
	v_pk_fma_f32 v[74:75], v[74:75], 0.5, v[226:227] op_sel_hi:[1,0,1]
	v_cvt_pk_bf16_f32 v240, v72, v73
	v_cvt_pk_bf16_f32 v241, v74, v75
	v_lshlrev_b32_e32 v156, 16, v240
	v_and_b32_e32 v157, 0xffff0000, v240
	v_lshlrev_b32_e32 v158, 16, v241
	v_and_b32_e32 v159, 0xffff0000, v241
	v_add_f32_e32 v164, v164, v156
	v_fmac_f32_e32 v165, v156, v156
	v_add_f32_e32 v164, v164, v157
	v_fmac_f32_e32 v165, v157, v157
	v_add_f32_e32 v164, v164, v158
	v_fmac_f32_e32 v165, v158, v158
	v_add_f32_e32 v164, v164, v159
	v_fmac_f32_e32 v165, v159, v159
	s_waitcnt vmcnt(26)
	v_pk_mul_f32 v[228:229], v[228:229], s[34:35] op_sel_hi:[1,0]
	v_pk_mul_f32 v[230:231], v[230:231], s[34:35] op_sel_hi:[1,0]
	v_pk_fma_f32 v[76:77], v[76:77], 0.5, v[228:229] op_sel_hi:[1,0,1]
	v_pk_fma_f32 v[78:79], v[78:79], 0.5, v[230:231] op_sel_hi:[1,0,1]
	v_cvt_pk_bf16_f32 v242, v76, v77
	v_cvt_pk_bf16_f32 v243, v78, v79
	v_lshlrev_b32_e32 v156, 16, v242
	v_and_b32_e32 v157, 0xffff0000, v242
	v_lshlrev_b32_e32 v158, 16, v243
	v_and_b32_e32 v159, 0xffff0000, v243
	v_add_f32_e32 v164, v164, v156
	v_fmac_f32_e32 v165, v156, v156
	v_add_f32_e32 v164, v164, v157
	v_fmac_f32_e32 v165, v157, v157
	v_add_f32_e32 v164, v164, v158
	v_fmac_f32_e32 v165, v158, v158
	v_add_f32_e32 v164, v164, v159
	v_fmac_f32_e32 v165, v159, v159
	v_permlane16_swap_b32_e32 v240, v242
	v_permlane16_swap_b32_e32 v241, v243
	global_store_dwordx4 v154, v[240:243], s[18:19]
	s_waitcnt vmcnt(26)
	v_pk_mul_f32 v[232:233], v[232:233], s[34:35] op_sel_hi:[1,0]
	v_pk_mul_f32 v[234:235], v[234:235], s[34:35] op_sel_hi:[1,0]
	v_pk_fma_f32 v[64:65], v[64:65], 0.5, v[232:233] op_sel_hi:[1,0,1]
	v_pk_fma_f32 v[66:67], v[66:67], 0.5, v[234:235] op_sel_hi:[1,0,1]
	v_cvt_pk_bf16_f32 v168, v64, v65
	v_cvt_pk_bf16_f32 v169, v66, v67
	v_lshlrev_b32_e32 v156, 16, v168
	v_and_b32_e32 v157, 0xffff0000, v168
	v_lshlrev_b32_e32 v158, 16, v169
	v_and_b32_e32 v159, 0xffff0000, v169
	v_add_f32_e32 v164, v164, v156
	v_fmac_f32_e32 v165, v156, v156
	v_add_f32_e32 v164, v164, v157
	v_fmac_f32_e32 v165, v157, v157
	v_add_f32_e32 v164, v164, v158
	v_fmac_f32_e32 v165, v158, v158
	v_add_f32_e32 v164, v164, v159
	v_fmac_f32_e32 v165, v159, v159
	s_waitcnt vmcnt(25)
; template <int EPI>
; __device__ __forceinline__ void gemm_phase(const u16* __restrict__ A, const u16* __restrict__ Bt, const int K,
;                                            const int nN, char* shm, const EpiArgs& ea) {
;     ...
;               for (int bj = 0; bj < 2; ++bj) {
;                 uint2 pk[2];
; #pragma unroll
;                 for (int n = 0; n < 2; ++n) {
;                   const int col = cb + bj * 128 + n * 16;
;                   f32x4 c = acc[ai][bj][m][n];
;                   float h[4];
;                   if (EPI == EPI_FFN1) {
;                     float4 rv = *(const float4*)(ea.res + (size_t)row * DM + col);
;                     h[0] = rv.x; h[1] = rv.y; h[2] = rv.z; h[3] = rv.w;
;                   } else {
;                     uint2 yv = *(const uint2*)((const char*)ea.yb + tl_off(row, col, DM >> 6));
;                     float4 gv = *(const float4*)(ea.lng + col);
;                     float4 bv = *(const float4*)(ea.lnb + col);
;                     h[0] = (bf_lo(yv.x) - mu) * rstd * gv.x + bv.x; h[1] = (bf_hi(yv.x) - mu) * rstd * gv.y + bv.y;
;                     h[2] = (bf_lo(yv.y) - mu) * rstd * gv.z + bv.z; h[3] = (bf_hi(yv.y) - mu) * rstd * gv.w + bv.w;
;                   }
;                   float y[4];
;                   if (EPI == EPI_OUT) {
;                     float4 bo = *(const float4*)(ea.bias + col);
;                     y[0] = ALPHA * h[0] + c[0] + bo.x; y[1] = ALPHA * h[1] + c[1] + bo.y;
;                     y[2] = ALPHA * h[2] + c[2] + bo.z; y[3] = ALPHA * h[3] + c[3] + bo.w;
;                   } else {
; #pragma unroll
;                     for (int j = 0; j < 4; ++j) y[j] = ALPHA * h[j] + 0.5f * c[j];
;                   }
;                   if (EPI == EPI_FFN2) {
;                     *(float4*)(ea.outf + (size_t)row * DM + col) = make_float4(y[0], y[1], y[2], y[3]);
;                   } else {
;                     pk[n] = make_uint2(pack2(y[0], y[1]), pack2(y[2], y[3]));
;                     float q0 = bf_lo(pk[n].x), q1 = bf_hi(pk[n].x), q2 = bf_lo(pk[n].y), q3 = bf_hi(pk[n].y);
;                     rs += (q0 + q1) + (q2 + q3);
;                     rq += (q0 * q0 + q1 * q1) + (q2 * q2 + q3 * q3);
;                   }
;                 }
;                 if (EPI != EPI_FFN2) {
;                   const uint4 w = widen16(pk[0], pk[1]);
	v_pk_mul_f32 v[236:237], v[236:237], s[34:35] op_sel_hi:[1,0]
	v_pk_mul_f32 v[238:239], v[238:239], s[34:35] op_sel_hi:[1,0]
	v_pk_fma_f32 v[68:69], v[68:69], 0.5, v[236:237] op_sel_hi:[1,0,1]
	v_pk_fma_f32 v[70:71], v[70:71], 0.5, v[238:239] op_sel_hi:[1,0,1]
	v_cvt_pk_bf16_f32 v170, v68, v69
	v_cvt_pk_bf16_f32 v171, v70, v71
	v_lshlrev_b32_e32 v156, 16, v170
	v_and_b32_e32 v157, 0xffff0000, v170
	v_lshlrev_b32_e32 v158, 16, v171
	v_and_b32_e32 v159, 0xffff0000, v171
	v_add_f32_e32 v164, v164, v156
	v_fmac_f32_e32 v165, v156, v156
	v_add_f32_e32 v164, v164, v157
	v_fmac_f32_e32 v165, v157, v157
	v_add_f32_e32 v164, v164, v158
	v_fmac_f32_e32 v165, v158, v158
	v_add_f32_e32 v164, v164, v159
	v_fmac_f32_e32 v165, v159, v159
	v_permlane16_swap_b32_e32 v168, v170
	v_permlane16_swap_b32_e32 v169, v171
	v_add_u32_e32 v152, 0x8000, v154
	global_store_dwordx4 v152, v[168:171], s[18:19]
	v_add_u32_e32 v153, 0x160000, v148
	global_load_dwordx4 v[224:227], v153, s[36:37]
	global_load_dwordx4 v[228:231], v153, s[36:37] offset:64
	global_load_dwordx4 v[232:235], v153, s[36:37] offset:512
	global_load_dwordx4 v[236:239], v153, s[36:37] offset:576
	v_mov_b32_e32 v166, v164
	v_mov_b32_e32 v167, v165
	s_nop 0
	v_permlane16_swap_b32_e32 v164, v166
	v_permlane16_swap_b32_e32 v165, v167
	v_add_f32_e32 v164, v164, v166
	v_add_f32_e32 v165, v165, v167
	v_mov_b32_e32 v166, v164
	v_mov_b32_e32 v167, v165
	s_nop 0
	v_permlane32_swap_b32_e32 v164, v166
	v_permlane32_swap_b32_e32 v165, v167
	v_add_f32_e32 v164, v164, v166
	v_add_f32_e32 v165, v165, v167
	s_and_saveexec_b64 s[26:27], s[6:7]
	global_atomic_add_f32 v150, v164, s[28:29] offset:384
	global_atomic_add_f32 v150, v165, s[28:29] offset:388
	s_or_b64 exec, exec, s[26:27]
	v_add_u32_e32 v154, 0x84000, v149
	v_mov_b32_e32 v164, 0
	v_mov_b32_e32 v165, 0
	s_waitcnt vmcnt(29)
	v_pk_mul_f32 v[176:177], v[176:177], s[34:35] op_sel_hi:[1,0]
	v_pk_mul_f32 v[178:179], v[178:179], s[34:35] op_sel_hi:[1,0]
	v_pk_fma_f32 v[56:57], v[56:57], 0.5, v[176:177] op_sel_hi:[1,0,1]
	v_pk_fma_f32 v[58:59], v[58:59], 0.5, v[178:179] op_sel_hi:[1,0,1]
	v_cvt_pk_bf16_f32 v240, v56, v57
	v_cvt_pk_bf16_f32 v241, v58, v59
	v_lshlrev_b32_e32 v156, 16, v240
	v_and_b32_e32 v157, 0xffff0000, v240
	v_lshlrev_b32_e32 v158, 16, v241
	v_and_b32_e32 v159, 0xffff0000, v241
	v_add_f32_e32 v164, v164, v156
	v_fmac_f32_e32 v165, v156, v156
	v_add_f32_e32 v164, v164, v157
	v_fmac_f32_e32 v165, v157, v157
	v_add_f32_e32 v164, v164, v158
	v_fmac_f32_e32 v165, v158, v158
	v_add_f32_e32 v164, v164, v159
	v_fmac_f32_e32 v165, v159, v159
	s_waitcnt vmcnt(28)
	v_pk_mul_f32 v[180:181], v[180:181], s[34:35] op_sel_hi:[1,0]
	v_pk_mul_f32 v[182:183], v[182:183], s[34:35] op_sel_hi:[1,0]
	v_pk_fma_f32 v[60:61], v[60:61], 0.5, v[180:181] op_sel_hi:[1,0,1]
	v_pk_fma_f32 v[62:63], v[62:63], 0.5, v[182:183] op_sel_hi:[1,0,1]
	v_cvt_pk_bf16_f32 v242, v60, v61
	v_cvt_pk_bf16_f32 v243, v62, v63
	v_lshlrev_b32_e32 v156, 16, v242
	v_and_b32_e32 v157, 0xffff0000, v242
	v_lshlrev_b32_e32 v158, 16, v243
	v_and_b32_e32 v159, 0xffff0000, v243
	v_add_f32_e32 v164, v164, v156
	v_fmac_f32_e32 v165, v156, v156
	v_add_f32_e32 v164, v164, v157
	v_fmac_f32_e32 v165, v157, v157
	v_add_f32_e32 v164, v164, v158
	v_fmac_f32_e32 v165, v158, v158
	v_add_f32_e32 v164, v164, v159
	v_fmac_f32_e32 v165, v159, v159
	v_permlane16_swap_b32_e32 v240, v242
	v_permlane16_swap_b32_e32 v241, v243
	global_store_dwordx4 v154, v[240:243], s[18:19]
	s_waitcnt vmcnt(28)
	v_pk_mul_f32 v[184:185], v[184:185], s[34:35] op_sel_hi:[1,0]
	v_pk_mul_f32 v[186:187], v[186:187], s[34:35] op_sel_hi:[1,0]
	v_pk_fma_f32 v[48:49], v[48:49], 0.5, v[184:185] op_sel_hi:[1,0,1]
	v_pk_fma_f32 v[50:51], v[50:51], 0.5, v[186:187] op_sel_hi:[1,0,1]
	v_cvt_pk_bf16_f32 v168, v48, v49
	v_cvt_pk_bf16_f32 v169, v50, v51
	v_lshlrev_b32_e32 v156, 16, v168
	v_and_b32_e32 v157, 0xffff0000, v168
	v_lshlrev_b32_e32 v158, 16, v169
	v_and_b32_e32 v159, 0xffff0000, v169
	v_add_f32_e32 v164, v164, v156
	v_fmac_f32_e32 v165, v156, v156
	v_add_f32_e32 v164, v164, v157
	v_fmac_f32_e32 v165, v157, v157
	v_add_f32_e32 v164, v164, v158
	v_fmac_f32_e32 v165, v158, v158
	v_add_f32_e32 v164, v164, v159
	v_fmac_f32_e32 v165, v159, v159
	s_waitcnt vmcnt(27)
	v_pk_mul_f32 v[188:189], v[188:189], s[34:35] op_sel_hi:[1,0]
	v_pk_mul_f32 v[190:191], v[190:191], s[34:35] op_sel_hi:[1,0]
	v_pk_fma_f32 v[52:53], v[52:53], 0.5, v[188:189] op_sel_hi:[1,0,1]
	v_pk_fma_f32 v[54:55], v[54:55], 0.5, v[190:191] op_sel_hi:[1,0,1]
	v_cvt_pk_bf16_f32 v170, v52, v53
	v_cvt_pk_bf16_f32 v171, v54, v55
	v_lshlrev_b32_e32 v156, 16, v170
	v_and_b32_e32 v157, 0xffff0000, v170
	v_lshlrev_b32_e32 v158, 16, v171
	v_and_b32_e32 v159, 0xffff0000, v171
	v_add_f32_e32 v164, v164, v156
	v_fmac_f32_e32 v165, v156, v156
	v_add_f32_e32 v164, v164, v157
	v_fmac_f32_e32 v165, v157, v157
	v_add_f32_e32 v164, v164, v158
	v_fmac_f32_e32 v165, v158, v158
	v_add_f32_e32 v164, v164, v159
	v_fmac_f32_e32 v165, v159, v159
	v_permlane16_swap_b32_e32 v168, v170
	v_permlane16_swap_b32_e32 v169, v171
	v_add_u32_e32 v152, 0x8000, v154
	global_store_dwordx4 v152, v[168:171], s[18:19]
	v_mov_b32_e32 v166, v164
	v_mov_b32_e32 v167, v165
	s_nop 0
	v_permlane16_swap_b32_e32 v164, v166
	v_permlane16_swap_b32_e32 v165, v167
	v_add_f32_e32 v164, v164, v166
	v_add_f32_e32 v165, v165, v167
	v_mov_b32_e32 v166, v164
	v_mov_b32_e32 v167, v165
	s_nop 0
	v_permlane32_swap_b32_e32 v164, v166
	v_permlane32_swap_b32_e32 v165, v167
	v_add_f32_e32 v164, v164, v166
	v_add_f32_e32 v165, v165, v167
	s_and_saveexec_b64 s[26:27], s[6:7]
	global_atomic_add_f32 v150, v164, s[28:29] offset:1024
	global_atomic_add_f32 v150, v165, s[28:29] offset:1028
	s_or_b64 exec, exec, s[26:27]
	v_add_u32_e32 v154, 0x84800, v149
	v_mov_b32_e32 v164, 0
	v_mov_b32_e32 v165, 0
	s_waitcnt vmcnt(25)
; template <int EPI>
; __device__ __forceinline__ void gemm_phase(const u16* __restrict__ A, const u16* __restrict__ Bt, const int K,
;                                            const int nN, char* shm, const EpiArgs& ea) {
;     ...
;               for (int bj = 0; bj < 2; ++bj) {
;                 uint2 pk[2];
; #pragma unroll
;                 for (int n = 0; n < 2; ++n) {
;                   const int col = cb + bj * 128 + n * 16;
;                   f32x4 c = acc[ai][bj][m][n];
;                   float h[4];
;                   if (EPI == EPI_FFN1) {
;                     float4 rv = *(const float4*)(ea.res + (size_t)row * DM + col);
;                     h[0] = rv.x; h[1] = rv.y; h[2] = rv.z; h[3] = rv.w;
;                   } else {
;                     uint2 yv = *(const uint2*)((const char*)ea.yb + tl_off(row, col, DM >> 6));
;                     float4 gv = *(const float4*)(ea.lng + col);
;                     float4 bv = *(const float4*)(ea.lnb + col);
;                     h[0] = (bf_lo(yv.x) - mu) * rstd * gv.x + bv.x; h[1] = (bf_hi(yv.x) - mu) * rstd * gv.y + bv.y;
;                     h[2] = (bf_lo(yv.y) - mu) * rstd * gv.z + bv.z; h[3] = (bf_hi(yv.y) - mu) * rstd * gv.w + bv.w;
;                   }
;                   float y[4];
;                   if (EPI == EPI_OUT) {
;                     float4 bo = *(const float4*)(ea.bias + col);
;                     y[0] = ALPHA * h[0] + c[0] + bo.x; y[1] = ALPHA * h[1] + c[1] + bo.y;
;                     y[2] = ALPHA * h[2] + c[2] + bo.z; y[3] = ALPHA * h[3] + c[3] + bo.w;
;                   } else {
; #pragma unroll
;                     for (int j = 0; j < 4; ++j) y[j] = ALPHA * h[j] + 0.5f * c[j];
;                   }
;                   if (EPI == EPI_FFN2) {
;                     *(float4*)(ea.outf + (size_t)row * DM + col) = make_float4(y[0], y[1], y[2], y[3]);
;                   } else {
;                     pk[n] = make_uint2(pack2(y[0], y[1]), pack2(y[2], y[3]));
;                     float q0 = bf_lo(pk[n].x), q1 = bf_hi(pk[n].x), q2 = bf_lo(pk[n].y), q3 = bf_hi(pk[n].y);
;                     rs += (q0 + q1) + (q2 + q3);
;                     rq += (q0 * q0 + q1 * q1) + (q2 * q2 + q3 * q3);
;                   }
;                 }
;                 if (EPI != EPI_FFN2) {
;                   const uint4 w = widen16(pk[0], pk[1]);
	v_pk_mul_f32 v[192:193], v[192:193], s[34:35] op_sel_hi:[1,0]
	v_pk_mul_f32 v[194:195], v[194:195], s[34:35] op_sel_hi:[1,0]
	v_pk_fma_f32 v[40:41], v[40:41], 0.5, v[192:193] op_sel_hi:[1,0,1]
	v_pk_fma_f32 v[42:43], v[42:43], 0.5, v[194:195] op_sel_hi:[1,0,1]
	v_cvt_pk_bf16_f32 v240, v40, v41
	v_cvt_pk_bf16_f32 v241, v42, v43
	v_lshlrev_b32_e32 v156, 16, v240
	v_and_b32_e32 v157, 0xffff0000, v240
	v_lshlrev_b32_e32 v158, 16, v241
	v_and_b32_e32 v159, 0xffff0000, v241
	v_add_f32_e32 v164, v164, v156
	v_fmac_f32_e32 v165, v156, v156
	v_add_f32_e32 v164, v164, v157
	v_fmac_f32_e32 v165, v157, v157
	v_add_f32_e32 v164, v164, v158
	v_fmac_f32_e32 v165, v158, v158
	v_add_f32_e32 v164, v164, v159
	v_fmac_f32_e32 v165, v159, v159
	s_waitcnt vmcnt(24)
	v_pk_mul_f32 v[196:197], v[196:197], s[34:35] op_sel_hi:[1,0]
	v_pk_mul_f32 v[198:199], v[198:199], s[34:35] op_sel_hi:[1,0]
	v_pk_fma_f32 v[44:45], v[44:45], 0.5, v[196:197] op_sel_hi:[1,0,1]
	v_pk_fma_f32 v[46:47], v[46:47], 0.5, v[198:199] op_sel_hi:[1,0,1]
	v_cvt_pk_bf16_f32 v242, v44, v45
	v_cvt_pk_bf16_f32 v243, v46, v47
	v_lshlrev_b32_e32 v156, 16, v242
	v_and_b32_e32 v157, 0xffff0000, v242
	v_lshlrev_b32_e32 v158, 16, v243
	v_and_b32_e32 v159, 0xffff0000, v243
	v_add_f32_e32 v164, v164, v156
	v_fmac_f32_e32 v165, v156, v156
	v_add_f32_e32 v164, v164, v157
	v_fmac_f32_e32 v165, v157, v157
	v_add_f32_e32 v164, v164, v158
	v_fmac_f32_e32 v165, v158, v158
	v_add_f32_e32 v164, v164, v159
	v_fmac_f32_e32 v165, v159, v159
	v_permlane16_swap_b32_e32 v240, v242
	v_permlane16_swap_b32_e32 v241, v243
	global_store_dwordx4 v154, v[240:243], s[18:19]
	s_waitcnt vmcnt(24)
	v_pk_mul_f32 v[200:201], v[200:201], s[34:35] op_sel_hi:[1,0]
	v_pk_mul_f32 v[202:203], v[202:203], s[34:35] op_sel_hi:[1,0]
	v_pk_fma_f32 v[32:33], v[32:33], 0.5, v[200:201] op_sel_hi:[1,0,1]
	v_pk_fma_f32 v[34:35], v[34:35], 0.5, v[202:203] op_sel_hi:[1,0,1]
	v_cvt_pk_bf16_f32 v168, v32, v33
	v_cvt_pk_bf16_f32 v169, v34, v35
	v_lshlrev_b32_e32 v156, 16, v168
	v_and_b32_e32 v157, 0xffff0000, v168
	v_lshlrev_b32_e32 v158, 16, v169
	v_and_b32_e32 v159, 0xffff0000, v169
	v_add_f32_e32 v164, v164, v156
	v_fmac_f32_e32 v165, v156, v156
	v_add_f32_e32 v164, v164, v157
	v_fmac_f32_e32 v165, v157, v157
	v_add_f32_e32 v164, v164, v158
	v_fmac_f32_e32 v165, v158, v158
	v_add_f32_e32 v164, v164, v159
	v_fmac_f32_e32 v165, v159, v159
	s_waitcnt vmcnt(23)
	v_pk_mul_f32 v[204:205], v[204:205], s[34:35] op_sel_hi:[1,0]
	v_pk_mul_f32 v[206:207], v[206:207], s[34:35] op_sel_hi:[1,0]
	v_pk_fma_f32 v[36:37], v[36:37], 0.5, v[204:205] op_sel_hi:[1,0,1]
	v_pk_fma_f32 v[38:39], v[38:39], 0.5, v[206:207] op_sel_hi:[1,0,1]
	v_cvt_pk_bf16_f32 v170, v36, v37
	v_cvt_pk_bf16_f32 v171, v38, v39
	v_lshlrev_b32_e32 v156, 16, v170
	v_and_b32_e32 v157, 0xffff0000, v170
	v_lshlrev_b32_e32 v158, 16, v171
	v_and_b32_e32 v159, 0xffff0000, v171
	v_add_f32_e32 v164, v164, v156
	v_fmac_f32_e32 v165, v156, v156
	v_add_f32_e32 v164, v164, v157
	v_fmac_f32_e32 v165, v157, v157
	v_add_f32_e32 v164, v164, v158
	v_fmac_f32_e32 v165, v158, v158
	v_add_f32_e32 v164, v164, v159
	v_fmac_f32_e32 v165, v159, v159
	v_permlane16_swap_b32_e32 v168, v170
	v_permlane16_swap_b32_e32 v169, v171
	v_add_u32_e32 v152, 0x8000, v154
	global_store_dwordx4 v152, v[168:171], s[18:19]
	v_mov_b32_e32 v166, v164
	v_mov_b32_e32 v167, v165
	s_nop 0
	v_permlane16_swap_b32_e32 v164, v166
	v_permlane16_swap_b32_e32 v165, v167
	v_add_f32_e32 v164, v164, v166
	v_add_f32_e32 v165, v165, v167
	v_mov_b32_e32 v166, v164
	v_mov_b32_e32 v167, v165
	s_nop 0
	v_permlane32_swap_b32_e32 v164, v166
	v_permlane32_swap_b32_e32 v165, v167
	v_add_f32_e32 v164, v164, v166
	v_add_f32_e32 v165, v165, v167
	s_and_saveexec_b64 s[26:27], s[6:7]
	global_atomic_add_f32 v150, v164, s[28:29] offset:1152
	global_atomic_add_f32 v150, v165, s[28:29] offset:1156
	s_or_b64 exec, exec, s[26:27]
	v_add_u32_e32 v154, 0x85000, v149
	v_mov_b32_e32 v164, 0
	v_mov_b32_e32 v165, 0
	s_waitcnt vmcnt(21)
	v_pk_mul_f32 v[208:209], v[208:209], s[34:35] op_sel_hi:[1,0]
	v_pk_mul_f32 v[210:211], v[210:211], s[34:35] op_sel_hi:[1,0]
	v_pk_fma_f32 v[24:25], v[24:25], 0.5, v[208:209] op_sel_hi:[1,0,1]
	v_pk_fma_f32 v[26:27], v[26:27], 0.5, v[210:211] op_sel_hi:[1,0,1]
	v_cvt_pk_bf16_f32 v240, v24, v25
	v_cvt_pk_bf16_f32 v241, v26, v27
	v_lshlrev_b32_e32 v156, 16, v240
	v_and_b32_e32 v157, 0xffff0000, v240
	v_lshlrev_b32_e32 v158, 16, v241
	v_and_b32_e32 v159, 0xffff0000, v241
	v_add_f32_e32 v164, v164, v156
	v_fmac_f32_e32 v165, v156, v156
	v_add_f32_e32 v164, v164, v157
	v_fmac_f32_e32 v165, v157, v157
	v_add_f32_e32 v164, v164, v158
	v_fmac_f32_e32 v165, v158, v158
	v_add_f32_e32 v164, v164, v159
	v_fmac_f32_e32 v165, v159, v159
	s_waitcnt vmcnt(20)
	v_pk_mul_f32 v[212:213], v[212:213], s[34:35] op_sel_hi:[1,0]
	v_pk_mul_f32 v[214:215], v[214:215], s[34:35] op_sel_hi:[1,0]
	v_pk_fma_f32 v[28:29], v[28:29], 0.5, v[212:213] op_sel_hi:[1,0,1]
	v_pk_fma_f32 v[30:31], v[30:31], 0.5, v[214:215] op_sel_hi:[1,0,1]
	v_cvt_pk_bf16_f32 v242, v28, v29
	v_cvt_pk_bf16_f32 v243, v30, v31
	v_lshlrev_b32_e32 v156, 16, v242
	v_and_b32_e32 v157, 0xffff0000, v242
	v_lshlrev_b32_e32 v158, 16, v243
	v_and_b32_e32 v159, 0xffff0000, v243
	v_add_f32_e32 v164, v164, v156
	v_fmac_f32_e32 v165, v156, v156
	v_add_f32_e32 v164, v164, v157
	v_fmac_f32_e32 v165, v157, v157
	v_add_f32_e32 v164, v164, v158
	v_fmac_f32_e32 v165, v158, v158
	v_add_f32_e32 v164, v164, v159
	v_fmac_f32_e32 v165, v159, v159
	v_permlane16_swap_b32_e32 v240, v242
	v_permlane16_swap_b32_e32 v241, v243
	global_store_dwordx4 v154, v[240:243], s[18:19]
	s_waitcnt vmcnt(20)
; template <int EPI>
; __device__ __forceinline__ void gemm_phase(const u16* __restrict__ A, const u16* __restrict__ Bt, const int K,
;                                            const int nN, char* shm, const EpiArgs& ea) {
;     ...
;               for (int bj = 0; bj < 2; ++bj) {
;                 uint2 pk[2];
; #pragma unroll
;                 for (int n = 0; n < 2; ++n) {
;                   const int col = cb + bj * 128 + n * 16;
;                   f32x4 c = acc[ai][bj][m][n];
;                   float h[4];
;                   if (EPI == EPI_FFN1) {
;                     float4 rv = *(const float4*)(ea.res + (size_t)row * DM + col);
;                     h[0] = rv.x; h[1] = rv.y; h[2] = rv.z; h[3] = rv.w;
;                   } else {
;                     uint2 yv = *(const uint2*)((const char*)ea.yb + tl_off(row, col, DM >> 6));
;                     float4 gv = *(const float4*)(ea.lng + col);
;                     float4 bv = *(const float4*)(ea.lnb + col);
;                     h[0] = (bf_lo(yv.x) - mu) * rstd * gv.x + bv.x; h[1] = (bf_hi(yv.x) - mu) * rstd * gv.y + bv.y;
;                     h[2] = (bf_lo(yv.y) - mu) * rstd * gv.z + bv.z; h[3] = (bf_hi(yv.y) - mu) * rstd * gv.w + bv.w;
;                   }
;                   float y[4];
;                   if (EPI == EPI_OUT) {
;                     float4 bo = *(const float4*)(ea.bias + col);
;                     y[0] = ALPHA * h[0] + c[0] + bo.x; y[1] = ALPHA * h[1] + c[1] + bo.y;
;                     y[2] = ALPHA * h[2] + c[2] + bo.z; y[3] = ALPHA * h[3] + c[3] + bo.w;
;                   } else {
; #pragma unroll
;                     for (int j = 0; j < 4; ++j) y[j] = ALPHA * h[j] + 0.5f * c[j];
;                   }
;                   if (EPI == EPI_FFN2) {
;                     *(float4*)(ea.outf + (size_t)row * DM + col) = make_float4(y[0], y[1], y[2], y[3]);
;                   } else {
;                     pk[n] = make_uint2(pack2(y[0], y[1]), pack2(y[2], y[3]));
;                     float q0 = bf_lo(pk[n].x), q1 = bf_hi(pk[n].x), q2 = bf_lo(pk[n].y), q3 = bf_hi(pk[n].y);
;                     rs += (q0 + q1) + (q2 + q3);
;                     rq += (q0 * q0 + q1 * q1) + (q2 * q2 + q3 * q3);
;                   }
;                 }
;                 if (EPI != EPI_FFN2) {
;                   const uint4 w = widen16(pk[0], pk[1]);
	v_pk_mul_f32 v[216:217], v[216:217], s[34:35] op_sel_hi:[1,0]
	v_pk_mul_f32 v[218:219], v[218:219], s[34:35] op_sel_hi:[1,0]
	v_pk_fma_f32 v[16:17], v[16:17], 0.5, v[216:217] op_sel_hi:[1,0,1]
	v_pk_fma_f32 v[18:19], v[18:19], 0.5, v[218:219] op_sel_hi:[1,0,1]
	v_cvt_pk_bf16_f32 v168, v16, v17
	v_cvt_pk_bf16_f32 v169, v18, v19
	v_lshlrev_b32_e32 v156, 16, v168
	v_and_b32_e32 v157, 0xffff0000, v168
	v_lshlrev_b32_e32 v158, 16, v169
	v_and_b32_e32 v159, 0xffff0000, v169
	v_add_f32_e32 v164, v164, v156
	v_fmac_f32_e32 v165, v156, v156
	v_add_f32_e32 v164, v164, v157
	v_fmac_f32_e32 v165, v157, v157
	v_add_f32_e32 v164, v164, v158
	v_fmac_f32_e32 v165, v158, v158
	v_add_f32_e32 v164, v164, v159
	v_fmac_f32_e32 v165, v159, v159
	s_waitcnt vmcnt(19)
	v_pk_mul_f32 v[220:221], v[220:221], s[34:35] op_sel_hi:[1,0]
	v_pk_mul_f32 v[222:223], v[222:223], s[34:35] op_sel_hi:[1,0]
	v_pk_fma_f32 v[20:21], v[20:21], 0.5, v[220:221] op_sel_hi:[1,0,1]
	v_pk_fma_f32 v[22:23], v[22:23], 0.5, v[222:223] op_sel_hi:[1,0,1]
	v_cvt_pk_bf16_f32 v170, v20, v21
	v_cvt_pk_bf16_f32 v171, v22, v23
	v_lshlrev_b32_e32 v156, 16, v170
	v_and_b32_e32 v157, 0xffff0000, v170
	v_lshlrev_b32_e32 v158, 16, v171
	v_and_b32_e32 v159, 0xffff0000, v171
	v_add_f32_e32 v164, v164, v156
	v_fmac_f32_e32 v165, v156, v156
	v_add_f32_e32 v164, v164, v157
	v_fmac_f32_e32 v165, v157, v157
	v_add_f32_e32 v164, v164, v158
	v_fmac_f32_e32 v165, v158, v158
	v_add_f32_e32 v164, v164, v159
	v_fmac_f32_e32 v165, v159, v159
	v_permlane16_swap_b32_e32 v168, v170
	v_permlane16_swap_b32_e32 v169, v171
	v_add_u32_e32 v152, 0x8000, v154
	global_store_dwordx4 v152, v[168:171], s[18:19]
	v_mov_b32_e32 v166, v164
	v_mov_b32_e32 v167, v165
	s_nop 0
	v_permlane16_swap_b32_e32 v164, v166
	v_permlane16_swap_b32_e32 v165, v167
	v_add_f32_e32 v164, v164, v166
	v_add_f32_e32 v165, v165, v167
	v_mov_b32_e32 v166, v164
	v_mov_b32_e32 v167, v165
	s_nop 0
	v_permlane32_swap_b32_e32 v164, v166
	v_permlane32_swap_b32_e32 v165, v167
	v_add_f32_e32 v164, v164, v166
	v_add_f32_e32 v165, v165, v167
	s_and_saveexec_b64 s[26:27], s[6:7]
	global_atomic_add_f32 v150, v164, s[28:29] offset:1280
	global_atomic_add_f32 v150, v165, s[28:29] offset:1284
	s_or_b64 exec, exec, s[26:27]
	v_add_u32_e32 v154, 0x85800, v149
	v_mov_b32_e32 v164, 0
	v_mov_b32_e32 v165, 0
	s_waitcnt vmcnt(17)
	v_pk_mul_f32 v[224:225], v[224:225], s[34:35] op_sel_hi:[1,0]
	v_pk_mul_f32 v[226:227], v[226:227], s[34:35] op_sel_hi:[1,0]
	v_pk_fma_f32 v[8:9], v[8:9], 0.5, v[224:225] op_sel_hi:[1,0,1]
	v_pk_fma_f32 v[10:11], v[10:11], 0.5, v[226:227] op_sel_hi:[1,0,1]
	v_cvt_pk_bf16_f32 v240, v8, v9
	v_cvt_pk_bf16_f32 v241, v10, v11
	v_lshlrev_b32_e32 v156, 16, v240
	v_and_b32_e32 v157, 0xffff0000, v240
	v_lshlrev_b32_e32 v158, 16, v241
	v_and_b32_e32 v159, 0xffff0000, v241
	v_add_f32_e32 v164, v164, v156
	v_fmac_f32_e32 v165, v156, v156
	v_add_f32_e32 v164, v164, v157
	v_fmac_f32_e32 v165, v157, v157
	v_add_f32_e32 v164, v164, v158
	v_fmac_f32_e32 v165, v158, v158
	v_add_f32_e32 v164, v164, v159
	v_fmac_f32_e32 v165, v159, v159
	s_waitcnt vmcnt(16)
	v_pk_mul_f32 v[228:229], v[228:229], s[34:35] op_sel_hi:[1,0]
	v_pk_mul_f32 v[230:231], v[230:231], s[34:35] op_sel_hi:[1,0]
	v_pk_fma_f32 v[12:13], v[12:13], 0.5, v[228:229] op_sel_hi:[1,0,1]
	v_pk_fma_f32 v[14:15], v[14:15], 0.5, v[230:231] op_sel_hi:[1,0,1]
	v_cvt_pk_bf16_f32 v242, v12, v13
	v_cvt_pk_bf16_f32 v243, v14, v15
	v_lshlrev_b32_e32 v156, 16, v242
	v_and_b32_e32 v157, 0xffff0000, v242
	v_lshlrev_b32_e32 v158, 16, v243
	v_and_b32_e32 v159, 0xffff0000, v243
	v_add_f32_e32 v164, v164, v156
	v_fmac_f32_e32 v165, v156, v156
	v_add_f32_e32 v164, v164, v157
	v_fmac_f32_e32 v165, v157, v157
	v_add_f32_e32 v164, v164, v158
	v_fmac_f32_e32 v165, v158, v158
	v_add_f32_e32 v164, v164, v159
	v_fmac_f32_e32 v165, v159, v159
	v_permlane16_swap_b32_e32 v240, v242
	v_permlane16_swap_b32_e32 v241, v243
	global_store_dwordx4 v154, v[240:243], s[18:19]
	s_waitcnt vmcnt(16)
	v_pk_mul_f32 v[232:233], v[232:233], s[34:35] op_sel_hi:[1,0]
	v_pk_mul_f32 v[234:235], v[234:235], s[34:35] op_sel_hi:[1,0]
	v_pk_fma_f32 v[0:1], v[0:1], 0.5, v[232:233] op_sel_hi:[1,0,1]
	v_pk_fma_f32 v[2:3], v[2:3], 0.5, v[234:235] op_sel_hi:[1,0,1]
	v_cvt_pk_bf16_f32 v168, v0, v1
	v_cvt_pk_bf16_f32 v169, v2, v3
	v_lshlrev_b32_e32 v156, 16, v168
	v_and_b32_e32 v157, 0xffff0000, v168
	v_lshlrev_b32_e32 v158, 16, v169
	v_and_b32_e32 v159, 0xffff0000, v169
	v_add_f32_e32 v164, v164, v156
	v_fmac_f32_e32 v165, v156, v156
	v_add_f32_e32 v164, v164, v157
	v_fmac_f32_e32 v165, v157, v157
	v_add_f32_e32 v164, v164, v158
	v_fmac_f32_e32 v165, v158, v158
	v_add_f32_e32 v164, v164, v159
	v_fmac_f32_e32 v165, v159, v159
	s_waitcnt vmcnt(15)
	v_pk_mul_f32 v[236:237], v[236:237], s[34:35] op_sel_hi:[1,0]
	v_pk_mul_f32 v[238:239], v[238:239], s[34:35] op_sel_hi:[1,0]
	v_pk_fma_f32 v[4:5], v[4:5], 0.5, v[236:237] op_sel_hi:[1,0,1]
	v_pk_fma_f32 v[6:7], v[6:7], 0.5, v[238:239] op_sel_hi:[1,0,1]
	v_cvt_pk_bf16_f32 v170, v4, v5
	v_cvt_pk_bf16_f32 v171, v6, v7
	v_lshlrev_b32_e32 v156, 16, v170
	v_and_b32_e32 v157, 0xffff0000, v170
	v_lshlrev_b32_e32 v158, 16, v171
	v_and_b32_e32 v159, 0xffff0000, v171
	v_add_f32_e32 v164, v164, v156
	v_fmac_f32_e32 v165, v156, v156
	v_add_f32_e32 v164, v164, v157
	v_fmac_f32_e32 v165, v157, v157
	v_add_f32_e32 v164, v164, v158
	v_fmac_f32_e32 v165, v158, v158
	v_add_f32_e32 v164, v164, v159
	v_fmac_f32_e32 v165, v159, v159
	v_permlane16_swap_b32_e32 v168, v170
	v_permlane16_swap_b32_e32 v169, v171
	v_add_u32_e32 v152, 0x8000, v154
	global_store_dwordx4 v152, v[168:171], s[18:19]
	v_mov_b32_e32 v166, v164
	v_mov_b32_e32 v167, v165
	s_nop 0
	v_permlane16_swap_b32_e32 v164, v166
	v_permlane16_swap_b32_e32 v165, v167
	v_add_f32_e32 v164, v164, v166
	v_add_f32_e32 v165, v165, v167
	v_mov_b32_e32 v166, v164
	v_mov_b32_e32 v167, v165
	s_nop 0
	v_permlane32_swap_b32_e32 v164, v166
	v_permlane32_swap_b32_e32 v165, v167
	v_add_f32_e32 v164, v164, v166
	v_add_f32_e32 v165, v165, v167
	s_and_saveexec_b64 s[26:27], s[6:7]
	global_atomic_add_f32 v150, v164, s[28:29] offset:1408
	global_atomic_add_f32 v150, v165, s[28:29] offset:1412
	s_or_b64 exec, exec, s[26:27]
	s_mov_b64 s[26:27], exec
	s_branch .LBB0_225
